# previous best + prologue: remaining weight-transpose tiles via the LDS-free 16-byte-store transpose (no barriers) and de-serialised context copy
# baseline (speedup 1.0000x reference)
.LBB0_618:
	v_readlane_b32 s0, v252, 33
	v_readlane_b32 s1, v252, 34
	s_andn2_b64 vcc, exec, s[0:1]
	s_cbranch_vccnz .LBB0_635
	v_readlane_b32 s10, v251, 0
	s_sub_u32 s98, s96, 0xd0
	s_subb_u32 s99, s97, 0
	s_load_dwordx2 s[60:61], s[98:99], 0x40
	v_readfirstlane_b32 s18, v166
	s_lshr_b32 s18, s18, 6
	v_and_b32_e32 v102, 63, v166
	v_lshlrev_b32_e32 v103, 4, v102
	v_lshlrev_b32_e32 v104, 13, v102
	s_lshr_b32 s11, s10, 3
	s_and_b32 s9, s10, 7
	s_lshl_b32 s20, s9, 19
	s_lshl_b32 s16, s11, 7
	s_add_u32 s20, s20, s16
	s_lshl_b32 s16, s18, 4
	s_add_u32 s20, s20, s16
	s_add_u32 s20, s20, 0x500000
	s_add_u32 s2, s88, s20
	s_addc_u32 s3, s89, 0
	s_lshl_b32 s20, s11, 6
	s_lshl_b32 s16, s18, 3
	s_add_u32 s20, s20, s16
	s_mul_i32 s20, s20, 0x2400
	s_lshl_b32 s16, s9, 10
	s_add_u32 s20, s20, s16
	s_add_u32 s20, s20, 0x400
	s_waitcnt lgkmcnt(0)
	s_add_u32 s0, s60, s20
	s_addc_u32 s1, s61, 0
	global_load_dwordx4 v[118:121], v103, s[0:1] nt
	s_add_u32 s0, s0, 0x2400
	s_addc_u32 s1, s1, 0
	global_load_dwordx4 v[122:125], v103, s[0:1] nt
	s_add_u32 s0, s0, 0x2400
	s_addc_u32 s1, s1, 0
	global_load_dwordx4 v[126:129], v103, s[0:1] nt
	s_add_u32 s0, s0, 0x2400
	s_addc_u32 s1, s1, 0
	global_load_dwordx4 v[130:133], v103, s[0:1] nt
	s_add_u32 s0, s0, 0x2400
	s_addc_u32 s1, s1, 0
	global_load_dwordx4 v[134:137], v103, s[0:1] nt
	s_add_u32 s0, s0, 0x2400
	s_addc_u32 s1, s1, 0
	global_load_dwordx4 v[138:141], v103, s[0:1] nt
	s_add_u32 s0, s0, 0x2400
	s_addc_u32 s1, s1, 0
	global_load_dwordx4 v[142:145], v103, s[0:1] nt
	s_add_u32 s0, s0, 0x2400
	s_addc_u32 s1, s1, 0
	global_load_dwordx4 v[146:149], v103, s[0:1] nt
	s_waitcnt vmcnt(0)
	v_cvt_pk_bf16_f32 v80, v118, v122
	v_cvt_pk_bf16_f32 v81, v126, v130
	v_cvt_pk_bf16_f32 v82, v134, v138
	v_cvt_pk_bf16_f32 v83, v142, v146
	v_cvt_pk_bf16_f32 v84, v119, v123
	v_cvt_pk_bf16_f32 v85, v127, v131
	v_cvt_pk_bf16_f32 v86, v135, v139
	v_cvt_pk_bf16_f32 v87, v143, v147
	v_cvt_pk_bf16_f32 v88, v120, v124
	v_cvt_pk_bf16_f32 v89, v128, v132
	v_cvt_pk_bf16_f32 v90, v136, v140
	v_cvt_pk_bf16_f32 v91, v144, v148
	v_cvt_pk_bf16_f32 v92, v121, v125
	v_cvt_pk_bf16_f32 v93, v129, v133
	v_cvt_pk_bf16_f32 v94, v137, v141
	v_cvt_pk_bf16_f32 v95, v145, v149
	global_store_dwordx4 v104, v[80:83], s[2:3]
	s_add_u32 s2, s2, 0x800
	s_addc_u32 s3, s3, 0
	global_store_dwordx4 v104, v[84:87], s[2:3]
	s_add_u32 s2, s2, 0x800
	s_addc_u32 s3, s3, 0
	global_store_dwordx4 v104, v[88:91], s[2:3]
	s_add_u32 s2, s2, 0x800
	s_addc_u32 s3, s3, 0
	global_store_dwordx4 v104, v[92:95], s[2:3]
